# FF1 GEMM: per-lane row scales cached in LDS after the first unit (later unit epilogues skip 8 loads + IEEE sqrt/div)
# speedup vs baseline: 1.0088x; 1.0041x over previous
_Z4mega4Args:
	s_mov_b64 s[58:59], s[0:1]
	s_mov_b32 s61, s2
	s_mov_b32 s32, 0
	s_load_dwordx16 s[68:83], s[0:1], 0x80
	s_load_dwordx2 s[10:11], s[0:1], 0xc0
	s_add_u32 s2, s58, 0xc8
	s_addc_u32 s3, s59, 0
	v_and_b32_e32 v1, 0x3ff, v0
	v_writelane_b32 v249, s2, 0
	v_readfirstlane_b32 s17, v1
	s_nop 0
	v_writelane_b32 v249, s3, 1
	s_movk_i32 s2, 0x80
	v_cmp_gt_u32_e32 vcc, s2, v1
	s_and_saveexec_b64 s[2:3], vcc
	v_lshl_add_u32 v2, v1, 2, 0
	v_add_u32_e32 v2, 0x23e00, v2
	v_mov_b32_e32 v3, 0
	ds_write_b32 v2, v3
	s_or_b64 exec, exec, s[2:3]
	s_load_dword s0, s[58:59], 0xc8
	s_waitcnt lgkmcnt(0)
	s_barrier
	s_add_u32 s88, s82, 0x4000
	s_getreg_b32 s4, hwreg(HW_REG_XCC_ID, 0, 4)
	v_writelane_b32 v249, s0, 2
	s_addc_u32 s89, s83, 0
	s_and_b32 s60, s4, 15
	v_cmp_eq_u32_e64 s[6:7], 0, v1
	s_mov_b64 s[4:5], exec
	s_nop 0
	v_writelane_b32 v249, s6, 3
	s_nop 1
	v_writelane_b32 v249, s7, 4
	s_and_b64 s[6:7], s[4:5], s[6:7]
	s_mov_b64 exec, s[6:7]
	s_cbranch_execz .LBB0_5
	s_mov_b64 s[6:7], exec
	v_mbcnt_lo_u32_b32 v2, s6, 0
	v_mbcnt_hi_u32_b32 v2, s7, v2
	v_cmp_eq_u32_e32 vcc, 0, v2
	s_and_b64 s[8:9], exec, vcc
	s_mov_b64 exec, s[8:9]
	s_cbranch_execz .LBB0_5
	s_lshl_b32 s8, s60, 8
	s_bcnt1_i32_b64 s6, s[6:7]
	v_mov_b32_e32 v2, s8
	v_mov_b32_e32 v3, s6
	global_atomic_add v2, v3, s[88:89] offset:1024

.LBB0_19:
	v_ashrrev_i32_e32 v17, 6, v6
	v_and_b32_e32 v7, 15, v6
	v_lshlrev_b32_e32 v19, 10, v17
	v_lshl_or_b32 v177, s4, 6, v7
	v_lshl_add_u32 v19, s4, 13, v19
	v_readlane_b32 s4, v252, 9
	v_readlane_b32 s5, v252, 10
	v_readlane_b32 s28, v253, 56
	s_and_b32 s4, s5, 0x60
	v_readlane_b32 s29, v253, 57
	v_ashrrev_i32_e32 v16, 1, v6
	v_and_b32_e32 v18, 48, v6
	v_lshlrev_b32_e32 v6, 2, v6
	s_lshr_b32 s5, s4, 3
	v_lshl_add_u64 v[8:9], s[28:29], 0, v[64:65]
	v_mov_b32_e32 v151, v65
	v_lshl_or_b32 v7, v7, 6, v18
	v_and_b32_e32 v6, 32, v6
	v_add_lshl_u32 v17, s5, v17, 10
	s_mov_b64 s[6:7], 0x80
	v_readlane_b32 s5, v251, 25
	v_lshl_add_u64 v[10:11], s[28:29], 0, v[150:151]
	v_mov_b32_e32 v155, v65
	v_bitop3_b32 v18, v7, v19, v6 bitop3:0xde
	v_bitop3_b32 v179, v17, v7, v6 bitop3:0xf6
	v_lshl_add_u64 v[6:7], v[8:9], 0, s[6:7]
	s_mov_b32 m0, s5
	v_readlane_b32 s5, v251, 26
	v_lshl_add_u64 v[12:13], s[0:1], 0, v[154:155]
	v_mov_b32_e32 v153, v65
	s_waitcnt vmcnt(2)
	s_barrier
	global_load_lds_dwordx4 v[6:7], off
	v_lshl_add_u64 v[6:7], v[10:11], 0, s[6:7]
	s_mov_b32 m0, s5
	v_lshl_add_u64 v[14:15], s[0:1], 0, v[152:153]
	global_load_lds_dwordx4 v[6:7], off
	v_lshl_add_u64 v[6:7], v[12:13], 0, s[6:7]
	s_mov_b32 m0, s92
	v_readlane_b32 s5, v251, 28
	global_load_lds_dwordx4 v[6:7], off
	v_lshl_add_u64 v[6:7], v[14:15], 0, s[6:7]
	v_readlane_b32 s6, v253, 58
	s_mov_b32 m0, s78
	v_readlane_b32 s7, v253, 59
	global_load_lds_dwordx4 v[6:7], off
	s_nop 0
	v_lshl_add_u64 v[6:7], s[6:7], 0, v[64:65]
	s_mov_b32 m0, s5
	v_readlane_b32 s5, v254, 49
	global_load_lds_dwordx4 v[6:7], off
	v_lshl_add_u64 v[6:7], s[6:7], 0, v[150:151]
	s_add_i32 m0, s25, 0x1e000
	v_and_b32_e32 v16, -8, v16
	global_load_lds_dwordx4 v[6:7], off
	v_lshlrev_b32_e32 v6, 14, v3
	v_and_b32_e32 v6, 0xffff8000, v6
	v_lshl_add_u32 v4, v4, 11, v6
	v_and_b32_e32 v3, 1, v3
	v_lshl_or_b32 v3, v3, 6, v4
	v_lshl_add_u32 v156, v5, 1, v3
	v_lshlrev_b32_e32 v3, 14, v0
	v_and_b32_e32 v3, 0xffff8000, v3
	s_waitcnt vmcnt(6)
	v_lshl_add_u32 v1, v1, 11, v3
	v_and_b32_e32 v0, 1, v0
	s_cmp_lt_u32 s5, 4
	v_lshl_or_b32 v0, v0, 6, v1
	s_cselect_b64 s[22:23], -1, 0
	v_add_u32_e32 v181, s4, v16
	v_mov_b32_e32 v157, v65
	v_lshl_add_u32 v158, v2, 1, v0
	v_mov_b32_e32 v159, v65
	s_mov_b32 s51, 0
	v_add_u32_e32 v182, 0, v18
	v_readlane_b32 s52, v253, 49
	v_readlane_b32 s4, v253, 50
	s_barrier
	v_readlane_b32 s5, v253, 51
	s_mov_b32 s32, 0
	s_branch .LBB0_22

.LBB0_32:
	s_cmp_lg_u32 s32, 0
	s_cbranch_scc1 .Lff1_cached
	v_lshlrev_b32_e32 v232, 2, v177
	v_add_u32_e32 v232, 0x20000, v232
	v_lshl_add_u32 v174, s4, 8, v177
	v_readlane_b32 s0, v249, 32
	v_or_b32_e32 v172, 16, v174
	v_ashrrev_i32_e32 v175, 31, v174
	v_readlane_b32 s1, v249, 33
	v_ashrrev_i32_e32 v173, 31, v172
	v_or_b32_e32 v170, 32, v174
	v_or_b32_e32 v168, 48, v174
	v_lshl_add_u64 v[130:131], v[174:175], 4, s[0:1]
	v_lshl_add_u64 v[132:133], v[172:173], 4, s[0:1]
	v_ashrrev_i32_e32 v171, 31, v170
	v_ashrrev_i32_e32 v169, 31, v168
	v_add_u32_e32 v166, 0x80, v174
	v_add_u32_e32 v164, 0x90, v174
	global_load_dwordx4 v[184:187], v[130:131], off
	global_load_dwordx4 v[188:191], v[132:133], off
	v_lshl_add_u64 v[130:131], v[170:171], 4, s[0:1]
	v_lshl_add_u64 v[132:133], v[168:169], 4, s[0:1]
	v_ashrrev_i32_e32 v167, 31, v166
	v_ashrrev_i32_e32 v165, 31, v164
	v_add_u32_e32 v162, 0xa0, v174
	v_add_u32_e32 v160, 0xb0, v174
	global_load_dwordx4 v[192:195], v[130:131], off
	global_load_dwordx4 v[146:149], v[132:133], off
	v_lshl_add_u64 v[130:131], v[166:167], 4, s[0:1]
	v_lshl_add_u64 v[132:133], v[164:165], 4, s[0:1]
	v_ashrrev_i32_e32 v163, 31, v162
	v_ashrrev_i32_e32 v161, 31, v160
	global_load_dwordx4 v[142:145], v[130:131], off
	global_load_dwordx4 v[138:141], v[132:133], off
	v_lshl_add_u64 v[130:131], v[162:163], 4, s[0:1]
	v_lshl_add_u64 v[132:133], v[160:161], 4, s[0:1]
	global_load_dwordx4 v[134:137], v[130:131], off
	s_nop 0
	global_load_dwordx4 v[130:133], v[132:133], off
	s_waitcnt vmcnt(0)
	v_mov_b32_e32 v196, v185
	v_mov_b32_e32 v197, v186
	v_mov_b32_e32 v185, v187
	v_pk_add_f32 v[184:185], v[196:197], v[184:185]
	s_mov_b32 s4, 0xf800000
	v_add_f32_e32 v176, v184, v185
	v_fmamk_f32 v176, v176, 0x3a800000, v234
	v_cmp_gt_f32_e32 vcc, s4, v176
	v_mul_f32_e32 v178, 0x4f800000, v176
	s_nop 0
	v_cndmask_b32_e32 v176, v176, v178, vcc
	v_sqrt_f32_e32 v178, v176
	s_nop 0
	v_add_u32_e32 v180, -1, v178
	v_fma_f32 v183, -v180, v178, v176
	v_cmp_ge_f32_e64 s[0:1], 0, v183
	v_add_u32_e32 v183, 1, v178
	s_nop 0
	v_cndmask_b32_e64 v180, v178, v180, s[0:1]
	v_fma_f32 v178, -v183, v178, v176
	v_cmp_lt_f32_e64 s[0:1], 0, v178
	s_nop 1
	v_cndmask_b32_e64 v178, v180, v183, s[0:1]
	v_mul_f32_e32 v180, 0x37800000, v178
	v_cndmask_b32_e32 v178, v178, v180, vcc
	v_cmp_class_f32_e32 vcc, v176, v235
	s_nop 1
	v_cndmask_b32_e32 v176, v178, v176, vcc
	v_div_scale_f32 v178, s[0:1], v176, v176, 1.0
	v_rcp_f32_e32 v180, v178
	s_nop 0
	v_fma_f32 v183, -v178, v180, 1.0
	v_fmac_f32_e32 v180, v183, v180
	v_div_scale_f32 v183, vcc, 1.0, v176, 1.0
	v_mul_f32_e32 v184, v183, v180
	v_fma_f32 v185, -v178, v184, v183
	v_fmac_f32_e32 v184, v185, v180
	v_fma_f32 v178, -v178, v184, v183
	v_div_fmas_f32 v178, v178, v180, v184
	v_mov_b32_e32 v184, v189
	v_mov_b32_e32 v185, v190
	v_mov_b32_e32 v189, v191
	v_pk_add_f32 v[184:185], v[184:185], v[188:189]
	v_div_fixup_f32 v176, v178, v176, 1.0
	ds_write_b32 v232, v176 offset:0
	v_add_f32_e32 v178, v184, v185
	v_fmamk_f32 v178, v178, 0x3a800000, v234
	v_cmp_gt_f32_e32 vcc, s4, v178
	v_mul_f32_e32 v180, 0x4f800000, v178
	v_pk_mul_f32 v[122:123], v[122:123], v[176:177] op_sel_hi:[1,0]
	v_cndmask_b32_e32 v178, v178, v180, vcc
	v_sqrt_f32_e32 v180, v178
	v_pk_mul_f32 v[126:127], v[126:127], v[176:177] op_sel_hi:[1,0]
	v_pk_mul_f32 v[124:125], v[124:125], v[176:177] op_sel_hi:[1,0]
	v_max_f32_e32 v122, 0, v122
	v_add_u32_e32 v183, -1, v180
	v_fma_f32 v184, -v183, v180, v178
	v_cmp_ge_f32_e64 s[0:1], 0, v184
	v_add_u32_e32 v184, 1, v180
	v_pk_mul_f32 v[128:129], v[128:129], v[176:177] op_sel_hi:[1,0]
	v_cndmask_b32_e64 v183, v180, v183, s[0:1]
	v_fma_f32 v180, -v184, v180, v178
	v_cmp_lt_f32_e64 s[0:1], 0, v180
	v_max_f32_e32 v123, 0, v123
	v_max_f32_e32 v124, 0, v124
	v_cndmask_b32_e64 v180, v183, v184, s[0:1]
	v_mul_f32_e32 v183, 0x37800000, v180
	v_cndmask_b32_e32 v180, v180, v183, vcc
	v_cmp_class_f32_e32 vcc, v178, v235
	v_max_f32_e32 v126, 0, v126
	v_max_f32_e32 v125, 0, v125
	v_cndmask_b32_e32 v178, v180, v178, vcc
	v_div_scale_f32 v180, s[0:1], v178, v178, 1.0
	v_rcp_f32_e32 v183, v180
	v_pk_mul_f32 v[116:117], v[116:117], v[176:177] op_sel_hi:[1,0]
	v_pk_mul_f32 v[114:115], v[114:115], v[176:177] op_sel_hi:[1,0]
	v_mul_f32_e32 v126, v126, v126
	v_fma_f32 v184, -v180, v183, 1.0
	v_fmac_f32_e32 v183, v184, v183
	v_div_scale_f32 v184, vcc, 1.0, v178, 1.0
	v_mul_f32_e32 v185, v184, v183
	v_fma_f32 v186, -v180, v185, v184
	v_fmac_f32_e32 v185, v186, v183
	v_fma_f32 v180, -v180, v185, v184
	v_div_fmas_f32 v180, v180, v183, v185
	v_mov_b32_e32 v184, v193
	v_mov_b32_e32 v185, v194
	v_mov_b32_e32 v193, v195
	v_pk_add_f32 v[184:185], v[184:185], v[192:193]
	v_div_fixup_f32 v178, v180, v178, 1.0
	ds_write_b32 v232, v178 offset:64
	v_add_f32_e32 v180, v184, v185
	v_fmamk_f32 v180, v180, 0x3a800000, v234
	v_cmp_gt_f32_e32 vcc, s4, v180
	v_mul_f32_e32 v183, 0x4f800000, v180
	v_mul_f32_e32 v125, v125, v125
	v_cndmask_b32_e32 v180, v180, v183, vcc
	v_sqrt_f32_e32 v183, v180
	v_pk_mul_f32 v[120:121], v[120:121], v[176:177] op_sel_hi:[1,0]
	v_pk_mul_f32 v[118:119], v[118:119], v[176:177] op_sel_hi:[1,0]
	v_max_f32_e32 v114, 0, v114
	v_add_u32_e32 v184, -1, v183
	v_fma_f32 v185, -v184, v183, v180
	v_cmp_ge_f32_e64 s[0:1], 0, v185
	v_add_u32_e32 v185, 1, v183
	v_max_f32_e32 v115, 0, v115
	v_cndmask_b32_e64 v184, v183, v184, s[0:1]
	v_fma_f32 v183, -v185, v183, v180
	v_cmp_lt_f32_e64 s[0:1], 0, v183
	v_max_f32_e32 v116, 0, v116
	v_max_f32_e32 v118, 0, v118
	v_cndmask_b32_e64 v183, v184, v185, s[0:1]
	v_mul_f32_e32 v184, 0x37800000, v183
	v_cndmask_b32_e32 v183, v183, v184, vcc
	v_cmp_class_f32_e32 vcc, v180, v235
	v_max_f32_e32 v117, 0, v117
	v_pk_mul_f32 v[106:107], v[106:107], v[178:179] op_sel_hi:[1,0]
	v_cndmask_b32_e32 v180, v183, v180, vcc
	v_div_scale_f32 v183, s[0:1], v180, v180, 1.0
	v_rcp_f32_e32 v184, v183
	v_mul_f32_e32 v118, v118, v118
	v_mul_f32_e32 v117, v117, v117
	v_pk_mul_f32 v[110:111], v[110:111], v[178:179] op_sel_hi:[1,0]
	v_fma_f32 v185, -v183, v184, 1.0
	v_fmac_f32_e32 v184, v185, v184
	v_div_scale_f32 v185, vcc, 1.0, v180, 1.0
	v_mul_f32_e32 v186, v185, v184
	v_fma_f32 v187, -v183, v186, v185
	v_fmac_f32_e32 v186, v187, v184
	v_fma_f32 v183, -v183, v186, v185
	v_div_fmas_f32 v183, v183, v184, v186
	v_mov_b32_e32 v184, v147
	v_mov_b32_e32 v185, v148
	v_mov_b32_e32 v147, v149
	v_pk_add_f32 v[146:147], v[184:185], v[146:147]
	v_div_fixup_f32 v180, v183, v180, 1.0
	ds_write_b32 v232, v180 offset:128
	v_add_f32_e32 v146, v146, v147
	v_fmamk_f32 v146, v146, 0x3a800000, v234
	v_cmp_gt_f32_e32 vcc, s4, v146
	v_mul_f32_e32 v147, 0x4f800000, v146
	v_pk_mul_f32 v[108:109], v[108:109], v[178:179] op_sel_hi:[1,0]
	v_cndmask_b32_e32 v146, v146, v147, vcc
	v_sqrt_f32_e32 v147, v146
	v_max_f32_e32 v106, 0, v106
	v_pk_mul_f32 v[112:113], v[112:113], v[178:179] op_sel_hi:[1,0]
	v_max_f32_e32 v107, 0, v107
	v_add_u32_e32 v148, -1, v147
	v_fma_f32 v149, -v148, v147, v146
	v_cmp_ge_f32_e64 s[0:1], 0, v149
	v_add_u32_e32 v149, 1, v147
	v_max_f32_e32 v108, 0, v108
	v_cndmask_b32_e64 v148, v147, v148, s[0:1]
	v_fma_f32 v147, -v149, v147, v146
	v_cmp_lt_f32_e64 s[0:1], 0, v147
	v_max_f32_e32 v110, 0, v110
	v_max_f32_e32 v109, 0, v109
	v_cndmask_b32_e64 v147, v148, v149, s[0:1]
	v_mul_f32_e32 v148, 0x37800000, v147
	v_cndmask_b32_e32 v147, v147, v148, vcc
	v_cmp_class_f32_e32 vcc, v146, v235
	v_pk_mul_f32 v[100:101], v[100:101], v[178:179] op_sel_hi:[1,0]
	v_pk_mul_f32 v[98:99], v[98:99], v[178:179] op_sel_hi:[1,0]
	v_cndmask_b32_e32 v146, v147, v146, vcc
	v_div_scale_f32 v147, s[0:1], v146, v146, 1.0
	v_rcp_f32_e32 v148, v147
	v_mul_f32_e32 v110, v110, v110
	v_mul_f32_e32 v109, v109, v109
	v_pk_mul_f32 v[104:105], v[104:105], v[178:179] op_sel_hi:[1,0]
	v_fma_f32 v149, -v147, v148, 1.0
	v_fmac_f32_e32 v148, v149, v148
	v_div_scale_f32 v149, vcc, 1.0, v146, 1.0
	v_mul_f32_e32 v183, v149, v148
	v_fma_f32 v184, -v147, v183, v149
	v_fmac_f32_e32 v183, v184, v148
	v_fma_f32 v147, -v147, v183, v149
	v_div_fmas_f32 v147, v147, v148, v183
	v_mov_b32_e32 v148, v143
	v_mov_b32_e32 v149, v144
	v_mov_b32_e32 v143, v145
	v_pk_add_f32 v[142:143], v[148:149], v[142:143]
	v_div_fixup_f32 v146, v147, v146, 1.0
	ds_write_b32 v232, v146 offset:192
	v_add_f32_e32 v142, v142, v143
	v_fmamk_f32 v142, v142, 0x3a800000, v234
	v_cmp_gt_f32_e32 vcc, s4, v142
	v_mul_f32_e32 v143, 0x4f800000, v142
	v_pk_mul_f32 v[102:103], v[102:103], v[178:179] op_sel_hi:[1,0]
	v_cndmask_b32_e32 v142, v142, v143, vcc
	v_sqrt_f32_e32 v143, v142
	v_max_f32_e32 v98, 0, v98
	v_max_f32_e32 v99, 0, v99
	v_max_f32_e32 v100, 0, v100
	v_add_u32_e32 v144, -1, v143
	v_fma_f32 v145, -v144, v143, v142
	v_cmp_ge_f32_e64 s[0:1], 0, v145
	v_add_u32_e32 v145, 1, v143
	v_max_f32_e32 v102, 0, v102
	v_cndmask_b32_e64 v144, v143, v144, s[0:1]
	v_fma_f32 v143, -v145, v143, v142
	v_cmp_lt_f32_e64 s[0:1], 0, v143
	v_max_f32_e32 v101, 0, v101
	v_pk_mul_f32 v[90:91], v[90:91], v[180:181] op_sel_hi:[1,0]
	v_cndmask_b32_e64 v143, v144, v145, s[0:1]
	v_mul_f32_e32 v144, 0x37800000, v143
	v_cndmask_b32_e32 v143, v143, v144, vcc
	v_cmp_class_f32_e32 vcc, v142, v235
	v_mul_f32_e32 v102, v102, v102
	v_mul_f32_e32 v101, v101, v101
	v_cndmask_b32_e32 v142, v143, v142, vcc
	v_div_scale_f32 v143, s[0:1], v142, v142, 1.0
	v_rcp_f32_e32 v144, v143
	v_pk_mul_f32 v[94:95], v[94:95], v[180:181] op_sel_hi:[1,0]
	v_pk_mul_f32 v[92:93], v[92:93], v[180:181] op_sel_hi:[1,0]
	v_max_f32_e32 v90, 0, v90
	v_fma_f32 v145, -v143, v144, 1.0
	v_fmac_f32_e32 v144, v145, v144
	v_div_scale_f32 v145, vcc, 1.0, v142, 1.0
	v_mul_f32_e32 v147, v145, v144
	v_fma_f32 v148, -v143, v147, v145
	v_fmac_f32_e32 v147, v148, v144
	v_fma_f32 v143, -v143, v147, v145
	v_div_fmas_f32 v143, v143, v144, v147
	v_mov_b32_e32 v144, v139
	v_mov_b32_e32 v145, v140
	v_mov_b32_e32 v139, v141
	v_pk_add_f32 v[138:139], v[144:145], v[138:139]
	v_div_fixup_f32 v142, v143, v142, 1.0
	ds_write_b32 v232, v142 offset:512
	v_add_f32_e32 v138, v138, v139
	v_fmamk_f32 v138, v138, 0x3a800000, v234
	v_cmp_gt_f32_e32 vcc, s4, v138
	v_mul_f32_e32 v139, 0x4f800000, v138
	v_pk_mul_f32 v[96:97], v[96:97], v[180:181] op_sel_hi:[1,0]
	v_cndmask_b32_e32 v138, v138, v139, vcc
	v_sqrt_f32_e32 v139, v138
	v_max_f32_e32 v91, 0, v91
	v_max_f32_e32 v92, 0, v92
	v_max_f32_e32 v94, 0, v94
	v_add_u32_e32 v140, -1, v139
	v_fma_f32 v141, -v140, v139, v138
	v_cmp_ge_f32_e64 s[0:1], 0, v141
	v_add_u32_e32 v141, 1, v139
	v_max_f32_e32 v93, 0, v93
	v_cndmask_b32_e64 v140, v139, v140, s[0:1]
	v_fma_f32 v139, -v141, v139, v138
	v_cmp_lt_f32_e64 s[0:1], 0, v139
	v_pk_mul_f32 v[84:85], v[84:85], v[180:181] op_sel_hi:[1,0]
	v_pk_mul_f32 v[82:83], v[82:83], v[180:181] op_sel_hi:[1,0]
	v_cndmask_b32_e64 v139, v140, v141, s[0:1]
	v_mul_f32_e32 v140, 0x37800000, v139
	v_cndmask_b32_e32 v139, v139, v140, vcc
	v_cmp_class_f32_e32 vcc, v138, v235
	v_mul_f32_e32 v94, v94, v94
	v_mul_f32_e32 v93, v93, v93
	v_cndmask_b32_e32 v138, v139, v138, vcc
	v_div_scale_f32 v139, s[0:1], v138, v138, 1.0
	v_rcp_f32_e32 v140, v139
	v_pk_mul_f32 v[88:89], v[88:89], v[180:181] op_sel_hi:[1,0]
	v_pk_mul_f32 v[86:87], v[86:87], v[180:181] op_sel_hi:[1,0]
	v_max_f32_e32 v82, 0, v82
	v_fma_f32 v141, -v139, v140, 1.0
	v_fmac_f32_e32 v140, v141, v140
	v_div_scale_f32 v141, vcc, 1.0, v138, 1.0
	v_mul_f32_e32 v143, v141, v140
	v_fma_f32 v144, -v139, v143, v141
	v_fmac_f32_e32 v143, v144, v140
	v_fma_f32 v139, -v139, v143, v141
	v_div_fmas_f32 v139, v139, v140, v143
	v_mov_b32_e32 v140, v135
	v_mov_b32_e32 v141, v136
	v_mov_b32_e32 v135, v137
	v_pk_add_f32 v[134:135], v[140:141], v[134:135]
	v_div_fixup_f32 v138, v139, v138, 1.0
	ds_write_b32 v232, v138 offset:576
	v_add_f32_e32 v134, v134, v135
	v_fmamk_f32 v134, v134, 0x3a800000, v234
	v_cmp_gt_f32_e32 vcc, s4, v134
	v_mul_f32_e32 v135, 0x4f800000, v134
	v_max_f32_e32 v83, 0, v83
	v_cndmask_b32_e32 v134, v134, v135, vcc
	v_sqrt_f32_e32 v135, v134
	v_max_f32_e32 v84, 0, v84
	v_max_f32_e32 v86, 0, v86
	v_max_f32_e32 v85, 0, v85
	v_add_u32_e32 v136, -1, v135
	v_fma_f32 v137, -v136, v135, v134
	v_cmp_ge_f32_e64 s[0:1], 0, v137
	v_add_u32_e32 v137, 1, v135
	v_pk_mul_f32 v[74:75], v[74:75], v[146:147] op_sel_hi:[1,0]
	v_cndmask_b32_e64 v136, v135, v136, s[0:1]
	v_fma_f32 v135, -v137, v135, v134
	v_cmp_lt_f32_e64 s[0:1], 0, v135
	v_mul_f32_e32 v86, v86, v86
	v_mul_f32_e32 v85, v85, v85
	v_cndmask_b32_e64 v135, v136, v137, s[0:1]
	v_mul_f32_e32 v136, 0x37800000, v135
	v_cndmask_b32_e32 v135, v135, v136, vcc
	v_cmp_class_f32_e32 vcc, v134, v235
	v_pk_mul_f32 v[78:79], v[78:79], v[146:147] op_sel_hi:[1,0]
	v_pk_mul_f32 v[76:77], v[76:77], v[146:147] op_sel_hi:[1,0]
	v_cndmask_b32_e32 v134, v135, v134, vcc
	v_div_scale_f32 v135, s[0:1], v134, v134, 1.0
	v_rcp_f32_e32 v136, v135
	v_max_f32_e32 v74, 0, v74
	v_pk_mul_f32 v[80:81], v[80:81], v[146:147] op_sel_hi:[1,0]
	v_max_f32_e32 v75, 0, v75
	v_fma_f32 v137, -v135, v136, 1.0
	v_fmac_f32_e32 v136, v137, v136
	v_div_scale_f32 v137, vcc, 1.0, v134, 1.0
	v_mul_f32_e32 v139, v137, v136
	v_fma_f32 v140, -v135, v139, v137
	v_fmac_f32_e32 v139, v140, v136
	v_fma_f32 v135, -v135, v139, v137
	v_div_fmas_f32 v135, v135, v136, v139
	v_mov_b32_e32 v136, v131
	v_mov_b32_e32 v137, v132
	v_mov_b32_e32 v131, v133
	v_pk_add_f32 v[130:131], v[136:137], v[130:131]
	v_div_fixup_f32 v134, v135, v134, 1.0
	ds_write_b32 v232, v134 offset:640
	v_add_f32_e32 v130, v130, v131
	v_fmamk_f32 v130, v130, 0x3a800000, v234
	v_cmp_gt_f32_e32 vcc, s4, v130
	v_mul_f32_e32 v131, 0x4f800000, v130
	v_max_f32_e32 v76, 0, v76
	v_cndmask_b32_e32 v130, v130, v131, vcc
	v_sqrt_f32_e32 v131, v130
	v_max_f32_e32 v78, 0, v78
	v_max_f32_e32 v77, 0, v77
	v_pk_mul_f32 v[68:69], v[68:69], v[146:147] op_sel_hi:[1,0]
	v_add_u32_e32 v132, -1, v131
	v_fma_f32 v133, -v132, v131, v130
	v_cmp_ge_f32_e64 s[0:1], 0, v133
	v_add_u32_e32 v133, 1, v131
	v_pk_mul_f32 v[66:67], v[66:67], v[146:147] op_sel_hi:[1,0]
	v_cndmask_b32_e64 v132, v131, v132, s[0:1]
	v_fma_f32 v131, -v133, v131, v130
	v_cmp_lt_f32_e64 s[0:1], 0, v131
	v_mul_f32_e32 v78, v78, v78
	v_mul_f32_e32 v77, v77, v77
	v_cndmask_b32_e64 v131, v132, v133, s[0:1]
	v_mul_f32_e32 v132, 0x37800000, v131
	v_cndmask_b32_e32 v131, v131, v132, vcc
	v_cmp_class_f32_e32 vcc, v130, v235
	v_pk_mul_f32 v[72:73], v[72:73], v[146:147] op_sel_hi:[1,0]
	v_pk_mul_f32 v[70:71], v[70:71], v[146:147] op_sel_hi:[1,0]
	v_cndmask_b32_e32 v130, v131, v130, vcc
	v_div_scale_f32 v131, s[0:1], v130, v130, 1.0
	v_rcp_f32_e32 v132, v131
	v_readlane_b32 s0, v249, 30
	v_readlane_b32 s1, v249, 31
	v_max_f32_e32 v66, 0, v66
	v_fma_f32 v133, -v131, v132, 1.0
	v_fmac_f32_e32 v132, v133, v132
	v_div_scale_f32 v133, vcc, 1.0, v130, 1.0
	v_mul_f32_e32 v135, v133, v132
	v_fma_f32 v136, -v131, v135, v133
	v_fmac_f32_e32 v135, v136, v132
	v_fma_f32 v131, -v131, v135, v133
	v_div_fmas_f32 v131, v131, v132, v135
	v_lshl_add_u32 v132, s52, 8, v181
	v_div_fixup_f32 v130, v131, v130, 1.0
	ds_write_b32 v232, v130 offset:704
	v_ashrrev_i32_e32 v133, 31, v132
	v_lshlrev_b64 v[136:137], 13, v[174:175]
	v_mul_f32_e32 v131, v122, v122
	v_max_f32_e32 v122, 0, v127
	v_lshl_add_u64 v[136:137], s[0:1], 0, v[136:137]
	v_lshlrev_b64 v[132:133], 1, v[132:133]
	v_mul_f32_e32 v122, v122, v122
	v_mul_f32_e32 v127, v123, v123
	v_max_f32_e32 v123, 0, v128
	v_mul_f32_e32 v128, v124, v124
	v_max_f32_e32 v124, 0, v129
	v_lshl_add_u64 v[136:137], v[136:137], 0, v[132:133]
	v_mul_f32_e32 v123, v123, v123
	v_mul_f32_e32 v124, v124, v124
	v_cvt_pk_bf16_f32 v122, v126, v122
	v_cvt_pk_bf16_f32 v123, v123, v124
	v_cvt_pk_bf16_f32 v124, v131, v127
	v_cvt_pk_bf16_f32 v125, v128, v125
	global_store_dwordx4 v[136:137], v[122:125], off
	v_max_f32_e32 v67, 0, v67
	v_max_f32_e32 v68, 0, v68
	v_mul_f32_e32 v122, v114, v114
	v_max_f32_e32 v114, 0, v119
	v_mul_f32_e32 v119, v115, v115
	v_max_f32_e32 v115, 0, v120
	v_mul_f32_e32 v120, v116, v116
	v_max_f32_e32 v116, 0, v121
	v_mul_f32_e32 v114, v114, v114
	v_mul_f32_e32 v115, v115, v115
	v_mul_f32_e32 v116, v116, v116
	v_cvt_pk_bf16_f32 v114, v118, v114
	v_cvt_pk_bf16_f32 v115, v115, v116
	v_cvt_pk_bf16_f32 v116, v122, v119
	v_cvt_pk_bf16_f32 v117, v120, v117
	global_store_dwordx4 v[136:137], v[114:117], off offset:256
	v_max_f32_e32 v70, 0, v70
	v_max_f32_e32 v69, 0, v69
	v_lshlrev_b64 v[114:115], 13, v[172:173]
	v_mul_f32_e32 v116, v106, v106
	v_max_f32_e32 v106, 0, v111
	v_lshl_add_u64 v[114:115], s[0:1], 0, v[114:115]
	v_mul_f32_e32 v106, v106, v106
	v_mul_f32_e32 v111, v107, v107
	v_max_f32_e32 v107, 0, v112
	v_mul_f32_e32 v112, v108, v108
	v_max_f32_e32 v108, 0, v113
	v_lshl_add_u64 v[114:115], v[114:115], 0, v[132:133]
	v_mul_f32_e32 v107, v107, v107
	v_mul_f32_e32 v108, v108, v108
	v_cvt_pk_bf16_f32 v106, v110, v106
	v_cvt_pk_bf16_f32 v107, v107, v108
	v_cvt_pk_bf16_f32 v108, v116, v111
	v_cvt_pk_bf16_f32 v109, v112, v109
	global_store_dwordx4 v[114:115], v[106:109], off
	v_pk_mul_f32 v[56:57], v[56:57], v[142:143] op_sel_hi:[1,0]
	v_mul_f32_e32 v70, v70, v70
	v_mul_f32_e32 v106, v98, v98
	v_max_f32_e32 v98, 0, v103
	v_mul_f32_e32 v103, v99, v99
	v_max_f32_e32 v99, 0, v104
	v_mul_f32_e32 v104, v100, v100
	v_max_f32_e32 v100, 0, v105
	v_mul_f32_e32 v98, v98, v98
	v_mul_f32_e32 v99, v99, v99
	v_mul_f32_e32 v100, v100, v100
	v_cvt_pk_bf16_f32 v98, v102, v98
	v_cvt_pk_bf16_f32 v99, v99, v100
	v_cvt_pk_bf16_f32 v100, v106, v103
	v_cvt_pk_bf16_f32 v101, v104, v101
	global_store_dwordx4 v[114:115], v[98:101], off offset:256
	v_mul_f32_e32 v69, v69, v69
	v_pk_mul_f32 v[60:61], v[60:61], v[142:143] op_sel_hi:[1,0]
	v_lshlrev_b64 v[98:99], 13, v[170:171]
	v_mul_f32_e32 v100, v90, v90
	v_max_f32_e32 v90, 0, v95
	v_lshl_add_u64 v[98:99], s[0:1], 0, v[98:99]
	v_mul_f32_e32 v90, v90, v90
	v_mul_f32_e32 v95, v91, v91
	v_max_f32_e32 v91, 0, v96
	v_mul_f32_e32 v96, v92, v92
	v_max_f32_e32 v92, 0, v97
	v_lshl_add_u64 v[98:99], v[98:99], 0, v[132:133]
	v_mul_f32_e32 v91, v91, v91
	v_mul_f32_e32 v92, v92, v92
	v_cvt_pk_bf16_f32 v90, v94, v90
	v_cvt_pk_bf16_f32 v91, v91, v92
	v_cvt_pk_bf16_f32 v92, v100, v95
	v_cvt_pk_bf16_f32 v93, v96, v93
	global_store_dwordx4 v[98:99], v[90:93], off
	v_pk_mul_f32 v[58:59], v[58:59], v[142:143] op_sel_hi:[1,0]
	v_max_f32_e32 v56, 0, v56
	v_mul_f32_e32 v90, v82, v82
	v_max_f32_e32 v82, 0, v87
	v_mul_f32_e32 v87, v83, v83
	v_max_f32_e32 v83, 0, v88
	v_mul_f32_e32 v88, v84, v84
	v_max_f32_e32 v84, 0, v89
	v_mul_f32_e32 v82, v82, v82
	v_mul_f32_e32 v83, v83, v83
	v_mul_f32_e32 v84, v84, v84
	v_cvt_pk_bf16_f32 v82, v86, v82
	v_cvt_pk_bf16_f32 v83, v83, v84
	v_cvt_pk_bf16_f32 v84, v90, v87
	v_cvt_pk_bf16_f32 v85, v88, v85
	global_store_dwordx4 v[98:99], v[82:85], off offset:256
	v_pk_mul_f32 v[62:63], v[62:63], v[142:143] op_sel_hi:[1,0]
	v_max_f32_e32 v57, 0, v57
	v_lshlrev_b64 v[82:83], 13, v[168:169]
	v_mul_f32_e32 v84, v74, v74
	v_max_f32_e32 v74, 0, v79
	v_lshl_add_u64 v[82:83], s[0:1], 0, v[82:83]
	v_mul_f32_e32 v74, v74, v74
	v_mul_f32_e32 v79, v75, v75
	v_max_f32_e32 v75, 0, v80
	v_mul_f32_e32 v80, v76, v76
	v_max_f32_e32 v76, 0, v81
	v_lshl_add_u64 v[82:83], v[82:83], 0, v[132:133]
	v_mul_f32_e32 v75, v75, v75
	v_mul_f32_e32 v76, v76, v76
	v_cvt_pk_bf16_f32 v74, v78, v74
	v_cvt_pk_bf16_f32 v75, v75, v76
	v_cvt_pk_bf16_f32 v76, v84, v79
	v_cvt_pk_bf16_f32 v77, v80, v77
	global_store_dwordx4 v[82:83], v[74:77], off
	v_max_f32_e32 v58, 0, v58
	v_max_f32_e32 v60, 0, v60
	v_mul_f32_e32 v74, v66, v66
	v_max_f32_e32 v66, 0, v71
	v_mul_f32_e32 v71, v67, v67
	v_max_f32_e32 v67, 0, v72
	v_mul_f32_e32 v72, v68, v68
	v_max_f32_e32 v68, 0, v73
	v_mul_f32_e32 v66, v66, v66
	v_mul_f32_e32 v67, v67, v67
	v_mul_f32_e32 v68, v68, v68
	v_cvt_pk_bf16_f32 v66, v70, v66
	v_cvt_pk_bf16_f32 v67, v67, v68
	v_cvt_pk_bf16_f32 v68, v74, v71
	v_cvt_pk_bf16_f32 v69, v72, v69
	global_store_dwordx4 v[82:83], v[66:69], off offset:256
	v_max_f32_e32 v59, 0, v59
	v_pk_mul_f32 v[50:51], v[50:51], v[142:143] op_sel_hi:[1,0]
	v_lshlrev_b64 v[66:67], 13, v[166:167]
	v_mul_f32_e32 v68, v56, v56
	v_max_f32_e32 v56, 0, v61
	v_lshl_add_u64 v[66:67], s[0:1], 0, v[66:67]
	v_mul_f32_e32 v56, v56, v56
	v_mul_f32_e32 v61, v57, v57
	v_max_f32_e32 v57, 0, v62
	v_mul_f32_e32 v62, v58, v58
	v_max_f32_e32 v58, 0, v63
	v_pk_mul_f32 v[48:49], v[48:49], v[142:143] op_sel_hi:[1,0]
	v_lshl_add_u64 v[66:67], v[66:67], 0, v[132:133]
	v_mul_f32_e32 v60, v60, v60
	v_mul_f32_e32 v57, v57, v57
	v_mul_f32_e32 v58, v58, v58
	v_mul_f32_e32 v59, v59, v59
	v_cvt_pk_bf16_f32 v56, v60, v56
	v_pk_mul_f32 v[54:55], v[54:55], v[142:143] op_sel_hi:[1,0]
	v_pk_mul_f32 v[52:53], v[52:53], v[142:143] op_sel_hi:[1,0]
	v_max_f32_e32 v48, 0, v48
	v_max_f32_e32 v49, 0, v49
	v_max_f32_e32 v50, 0, v50
	v_cvt_pk_bf16_f32 v57, v57, v58
	v_cvt_pk_bf16_f32 v58, v68, v61
	v_cvt_pk_bf16_f32 v59, v62, v59
	global_store_dwordx4 v[66:67], v[56:59], off
	v_max_f32_e32 v52, 0, v52
	v_max_f32_e32 v51, 0, v51
	v_mul_f32_e32 v56, v48, v48
	v_max_f32_e32 v48, 0, v53
	v_mul_f32_e32 v53, v49, v49
	v_max_f32_e32 v49, 0, v54
	v_mul_f32_e32 v54, v50, v50
	v_max_f32_e32 v50, 0, v55
	v_mul_f32_e32 v48, v48, v48
	v_mul_f32_e32 v49, v49, v49
	v_mul_f32_e32 v50, v50, v50
	v_pk_mul_f32 v[40:41], v[40:41], v[138:139] op_sel_hi:[1,0]
	v_mul_f32_e32 v52, v52, v52
	v_mul_f32_e32 v51, v51, v51
	v_cvt_pk_bf16_f32 v48, v52, v48
	v_cvt_pk_bf16_f32 v49, v49, v50
	v_cvt_pk_bf16_f32 v50, v56, v53
	v_pk_mul_f32 v[44:45], v[44:45], v[138:139] op_sel_hi:[1,0]
	v_pk_mul_f32 v[42:43], v[42:43], v[138:139] op_sel_hi:[1,0]
	v_max_f32_e32 v40, 0, v40
	v_cvt_pk_bf16_f32 v51, v54, v51
	global_store_dwordx4 v[66:67], v[48:51], off offset:256
	v_pk_mul_f32 v[46:47], v[46:47], v[138:139] op_sel_hi:[1,0]
	v_max_f32_e32 v41, 0, v41
	v_lshlrev_b64 v[48:49], 13, v[164:165]
	v_mul_f32_e32 v50, v40, v40
	v_max_f32_e32 v40, 0, v45
	v_max_f32_e32 v42, 0, v42
	v_lshl_add_u64 v[48:49], s[0:1], 0, v[48:49]
	v_max_f32_e32 v44, 0, v44
	v_mul_f32_e32 v40, v40, v40
	v_mul_f32_e32 v45, v41, v41
	v_max_f32_e32 v41, 0, v46
	v_mul_f32_e32 v46, v42, v42
	v_max_f32_e32 v42, 0, v47
	v_max_f32_e32 v43, 0, v43
	v_pk_mul_f32 v[34:35], v[34:35], v[138:139] op_sel_hi:[1,0]
	v_pk_mul_f32 v[32:33], v[32:33], v[138:139] op_sel_hi:[1,0]
	v_lshl_add_u64 v[48:49], v[48:49], 0, v[132:133]
	v_mul_f32_e32 v44, v44, v44
	v_mul_f32_e32 v41, v41, v41
	v_mul_f32_e32 v42, v42, v42
	v_mul_f32_e32 v43, v43, v43
	v_cvt_pk_bf16_f32 v40, v44, v40
	v_pk_mul_f32 v[38:39], v[38:39], v[138:139] op_sel_hi:[1,0]
	v_pk_mul_f32 v[36:37], v[36:37], v[138:139] op_sel_hi:[1,0]
	v_max_f32_e32 v32, 0, v32
	v_max_f32_e32 v33, 0, v33
	v_max_f32_e32 v34, 0, v34
	v_cvt_pk_bf16_f32 v41, v41, v42
	v_cvt_pk_bf16_f32 v42, v50, v45
	v_cvt_pk_bf16_f32 v43, v46, v43
	global_store_dwordx4 v[48:49], v[40:43], off
	v_max_f32_e32 v36, 0, v36
	v_max_f32_e32 v35, 0, v35
	v_mul_f32_e32 v40, v32, v32
	v_max_f32_e32 v32, 0, v37
	v_mul_f32_e32 v37, v33, v33
	v_max_f32_e32 v33, 0, v38
	v_mul_f32_e32 v38, v34, v34
	v_max_f32_e32 v34, 0, v39
	v_mul_f32_e32 v32, v32, v32
	v_mul_f32_e32 v33, v33, v33
	v_mul_f32_e32 v34, v34, v34
	v_pk_mul_f32 v[24:25], v[24:25], v[134:135] op_sel_hi:[1,0]
	v_mul_f32_e32 v36, v36, v36
	v_mul_f32_e32 v35, v35, v35
	v_cvt_pk_bf16_f32 v32, v36, v32
	v_cvt_pk_bf16_f32 v33, v33, v34
	v_cvt_pk_bf16_f32 v34, v40, v37
	v_pk_mul_f32 v[28:29], v[28:29], v[134:135] op_sel_hi:[1,0]
	v_pk_mul_f32 v[26:27], v[26:27], v[134:135] op_sel_hi:[1,0]
	v_max_f32_e32 v24, 0, v24
	v_cvt_pk_bf16_f32 v35, v38, v35
	global_store_dwordx4 v[48:49], v[32:35], off offset:256
	v_pk_mul_f32 v[30:31], v[30:31], v[134:135] op_sel_hi:[1,0]
	v_max_f32_e32 v25, 0, v25
	v_lshlrev_b64 v[32:33], 13, v[162:163]
	v_mul_f32_e32 v34, v24, v24
	v_max_f32_e32 v24, 0, v29
	v_max_f32_e32 v26, 0, v26
	v_lshl_add_u64 v[32:33], s[0:1], 0, v[32:33]
	v_max_f32_e32 v28, 0, v28
	v_mul_f32_e32 v24, v24, v24
	v_mul_f32_e32 v29, v25, v25
	v_max_f32_e32 v25, 0, v30
	v_mul_f32_e32 v30, v26, v26
	v_max_f32_e32 v26, 0, v31
	v_max_f32_e32 v27, 0, v27
	v_pk_mul_f32 v[18:19], v[18:19], v[134:135] op_sel_hi:[1,0]
	v_pk_mul_f32 v[16:17], v[16:17], v[134:135] op_sel_hi:[1,0]
	v_lshl_add_u64 v[32:33], v[32:33], 0, v[132:133]
	v_mul_f32_e32 v28, v28, v28
	v_mul_f32_e32 v25, v25, v25
	v_mul_f32_e32 v26, v26, v26
	v_mul_f32_e32 v27, v27, v27
	v_cvt_pk_bf16_f32 v24, v28, v24
	v_pk_mul_f32 v[22:23], v[22:23], v[134:135] op_sel_hi:[1,0]
	v_pk_mul_f32 v[20:21], v[20:21], v[134:135] op_sel_hi:[1,0]
	v_max_f32_e32 v16, 0, v16
	v_max_f32_e32 v17, 0, v17
	v_max_f32_e32 v18, 0, v18
	v_cvt_pk_bf16_f32 v25, v25, v26
	v_cvt_pk_bf16_f32 v26, v34, v29
	v_cvt_pk_bf16_f32 v27, v30, v27
	global_store_dwordx4 v[32:33], v[24:27], off
	v_max_f32_e32 v20, 0, v20
	v_max_f32_e32 v19, 0, v19
	v_mul_f32_e32 v24, v16, v16
	v_max_f32_e32 v16, 0, v21
	v_mul_f32_e32 v21, v17, v17
	v_max_f32_e32 v17, 0, v22
	v_mul_f32_e32 v22, v18, v18
	v_max_f32_e32 v18, 0, v23
	v_mul_f32_e32 v16, v16, v16
	v_mul_f32_e32 v17, v17, v17
	v_mul_f32_e32 v18, v18, v18
	v_pk_mul_f32 v[8:9], v[8:9], v[130:131] op_sel_hi:[1,0]
	v_mul_f32_e32 v20, v20, v20
	v_mul_f32_e32 v19, v19, v19
	v_cvt_pk_bf16_f32 v16, v20, v16
	v_cvt_pk_bf16_f32 v17, v17, v18
	v_cvt_pk_bf16_f32 v18, v24, v21
	v_pk_mul_f32 v[12:13], v[12:13], v[130:131] op_sel_hi:[1,0]
	v_pk_mul_f32 v[10:11], v[10:11], v[130:131] op_sel_hi:[1,0]
	v_max_f32_e32 v8, 0, v8
	v_cvt_pk_bf16_f32 v19, v22, v19
	global_store_dwordx4 v[32:33], v[16:19], off offset:256
	v_pk_mul_f32 v[14:15], v[14:15], v[130:131] op_sel_hi:[1,0]
	v_max_f32_e32 v9, 0, v9
	v_lshlrev_b64 v[16:17], 13, v[160:161]
	v_mul_f32_e32 v18, v8, v8
	v_max_f32_e32 v8, 0, v13
	v_max_f32_e32 v10, 0, v10
	v_lshl_add_u64 v[16:17], s[0:1], 0, v[16:17]
	v_max_f32_e32 v12, 0, v12
	v_mul_f32_e32 v8, v8, v8
	v_mul_f32_e32 v13, v9, v9
	v_max_f32_e32 v9, 0, v14
	v_mul_f32_e32 v14, v10, v10
	v_max_f32_e32 v10, 0, v15
	v_max_f32_e32 v11, 0, v11
	v_pk_mul_f32 v[2:3], v[2:3], v[130:131] op_sel_hi:[1,0]
	v_pk_mul_f32 v[0:1], v[0:1], v[130:131] op_sel_hi:[1,0]
	v_lshl_add_u64 v[16:17], v[16:17], 0, v[132:133]
	v_mul_f32_e32 v12, v12, v12
	v_mul_f32_e32 v9, v9, v9
	v_mul_f32_e32 v10, v10, v10
	v_mul_f32_e32 v11, v11, v11
	v_cvt_pk_bf16_f32 v8, v12, v8
	v_pk_mul_f32 v[6:7], v[6:7], v[130:131] op_sel_hi:[1,0]
	v_pk_mul_f32 v[4:5], v[4:5], v[130:131] op_sel_hi:[1,0]
	v_max_f32_e32 v0, 0, v0
	v_max_f32_e32 v1, 0, v1
	v_max_f32_e32 v2, 0, v2
	v_cvt_pk_bf16_f32 v9, v9, v10
	v_cvt_pk_bf16_f32 v10, v18, v13
	v_cvt_pk_bf16_f32 v11, v14, v11
	global_store_dwordx4 v[16:17], v[8:11], off
	v_max_f32_e32 v3, 0, v3
	v_max_f32_e32 v4, 0, v4
	v_mul_f32_e32 v8, v0, v0
	v_max_f32_e32 v0, 0, v5
	v_mul_f32_e32 v5, v1, v1
	v_max_f32_e32 v1, 0, v6
	v_mul_f32_e32 v6, v2, v2
	v_max_f32_e32 v2, 0, v7
	v_mul_f32_e32 v0, v0, v0
	v_mul_f32_e32 v1, v1, v1
	v_mul_f32_e32 v2, v2, v2
	v_mul_f32_e32 v3, v3, v3
	s_mov_b64 s[0:1], -1
	s_andn2_b64 vcc, exec, s[42:43]
	v_mul_f32_e32 v4, v4, v4
	v_cvt_pk_bf16_f32 v0, v4, v0
	v_cvt_pk_bf16_f32 v1, v1, v2
	v_cvt_pk_bf16_f32 v2, v8, v5
	v_cvt_pk_bf16_f32 v3, v6, v3
	global_store_dwordx4 v[16:17], v[0:3], off offset:256
	s_mov_b32 s32, 1
.Lff1_join:
	s_cbranch_vccnz .LBB0_21
	s_andn2_b64 vcc, exec, s[2:3]
	s_cbranch_vccnz .LBB0_20
	s_barrier
	s_branch .LBB0_20
.Lff1_cached:
	v_lshlrev_b32_e32 v232, 2, v177
	v_add_u32_e32 v232, 0x20000, v232
	ds_read_b32 v176, v232 offset:0
	ds_read_b32 v178, v232 offset:64
	ds_read_b32 v180, v232 offset:128
	ds_read_b32 v146, v232 offset:192
	ds_read_b32 v142, v232 offset:512
	ds_read_b32 v138, v232 offset:576
	ds_read_b32 v134, v232 offset:640
	ds_read_b32 v130, v232 offset:704
	s_waitcnt lgkmcnt(0)
	v_lshl_add_u32 v174, s4, 8, v177
	v_or_b32_e32 v172, 16, v174
	v_ashrrev_i32_e32 v175, 31, v174
	v_ashrrev_i32_e32 v173, 31, v172
	v_or_b32_e32 v170, 32, v174
	v_or_b32_e32 v168, 48, v174
	v_ashrrev_i32_e32 v171, 31, v170
	v_ashrrev_i32_e32 v169, 31, v168
	v_add_u32_e32 v166, 0x80, v174
	v_add_u32_e32 v164, 0x90, v174
	v_ashrrev_i32_e32 v167, 31, v166
	v_ashrrev_i32_e32 v165, 31, v164
	v_add_u32_e32 v162, 0xa0, v174
	v_add_u32_e32 v160, 0xb0, v174
	v_ashrrev_i32_e32 v163, 31, v162
	v_ashrrev_i32_e32 v161, 31, v160
	s_nop 0
	s_waitcnt vmcnt(0)
	s_nop 0
	s_nop 0
	s_nop 0
	s_nop 1
	s_nop 1
	s_nop 0
	v_pk_mul_f32 v[122:123], v[122:123], v[176:177] op_sel_hi:[1,0]
	v_pk_mul_f32 v[126:127], v[126:127], v[176:177] op_sel_hi:[1,0]
	v_pk_mul_f32 v[124:125], v[124:125], v[176:177] op_sel_hi:[1,0]
	v_max_f32_e32 v122, 0, v122
	v_pk_mul_f32 v[128:129], v[128:129], v[176:177] op_sel_hi:[1,0]
	v_max_f32_e32 v123, 0, v123
	v_max_f32_e32 v124, 0, v124
	v_max_f32_e32 v126, 0, v126
	v_max_f32_e32 v125, 0, v125
	v_pk_mul_f32 v[116:117], v[116:117], v[176:177] op_sel_hi:[1,0]
	v_pk_mul_f32 v[114:115], v[114:115], v[176:177] op_sel_hi:[1,0]
	v_mul_f32_e32 v126, v126, v126
	v_mul_f32_e32 v125, v125, v125
	v_pk_mul_f32 v[120:121], v[120:121], v[176:177] op_sel_hi:[1,0]
	v_pk_mul_f32 v[118:119], v[118:119], v[176:177] op_sel_hi:[1,0]
	v_max_f32_e32 v114, 0, v114
	v_max_f32_e32 v115, 0, v115
	v_max_f32_e32 v116, 0, v116
	v_max_f32_e32 v118, 0, v118
	v_max_f32_e32 v117, 0, v117
	v_pk_mul_f32 v[106:107], v[106:107], v[178:179] op_sel_hi:[1,0]
	v_mul_f32_e32 v118, v118, v118
	v_mul_f32_e32 v117, v117, v117
	v_pk_mul_f32 v[110:111], v[110:111], v[178:179] op_sel_hi:[1,0]
	v_pk_mul_f32 v[108:109], v[108:109], v[178:179] op_sel_hi:[1,0]
	v_max_f32_e32 v106, 0, v106
	v_pk_mul_f32 v[112:113], v[112:113], v[178:179] op_sel_hi:[1,0]
	v_max_f32_e32 v107, 0, v107
	v_max_f32_e32 v108, 0, v108
	v_max_f32_e32 v110, 0, v110
	v_max_f32_e32 v109, 0, v109
	v_pk_mul_f32 v[100:101], v[100:101], v[178:179] op_sel_hi:[1,0]
	v_pk_mul_f32 v[98:99], v[98:99], v[178:179] op_sel_hi:[1,0]
	v_mul_f32_e32 v110, v110, v110
	v_mul_f32_e32 v109, v109, v109
	v_pk_mul_f32 v[104:105], v[104:105], v[178:179] op_sel_hi:[1,0]
	v_pk_mul_f32 v[102:103], v[102:103], v[178:179] op_sel_hi:[1,0]
	v_max_f32_e32 v98, 0, v98
	v_max_f32_e32 v99, 0, v99
	v_max_f32_e32 v100, 0, v100
	v_max_f32_e32 v102, 0, v102
	v_max_f32_e32 v101, 0, v101
	v_pk_mul_f32 v[90:91], v[90:91], v[180:181] op_sel_hi:[1,0]
	v_mul_f32_e32 v102, v102, v102
	v_mul_f32_e32 v101, v101, v101
	v_pk_mul_f32 v[94:95], v[94:95], v[180:181] op_sel_hi:[1,0]
	v_pk_mul_f32 v[92:93], v[92:93], v[180:181] op_sel_hi:[1,0]
	v_max_f32_e32 v90, 0, v90
	v_pk_mul_f32 v[96:97], v[96:97], v[180:181] op_sel_hi:[1,0]
	v_max_f32_e32 v91, 0, v91
	v_max_f32_e32 v92, 0, v92
	v_max_f32_e32 v94, 0, v94
	v_max_f32_e32 v93, 0, v93
	v_pk_mul_f32 v[84:85], v[84:85], v[180:181] op_sel_hi:[1,0]
	v_pk_mul_f32 v[82:83], v[82:83], v[180:181] op_sel_hi:[1,0]
	v_mul_f32_e32 v94, v94, v94
	v_mul_f32_e32 v93, v93, v93
	v_pk_mul_f32 v[88:89], v[88:89], v[180:181] op_sel_hi:[1,0]
	v_pk_mul_f32 v[86:87], v[86:87], v[180:181] op_sel_hi:[1,0]
	v_max_f32_e32 v82, 0, v82
	v_max_f32_e32 v83, 0, v83
	v_max_f32_e32 v84, 0, v84
	v_max_f32_e32 v86, 0, v86
	v_max_f32_e32 v85, 0, v85
	v_pk_mul_f32 v[74:75], v[74:75], v[146:147] op_sel_hi:[1,0]
	v_mul_f32_e32 v86, v86, v86
	v_mul_f32_e32 v85, v85, v85
	v_pk_mul_f32 v[78:79], v[78:79], v[146:147] op_sel_hi:[1,0]
	v_pk_mul_f32 v[76:77], v[76:77], v[146:147] op_sel_hi:[1,0]
	v_max_f32_e32 v74, 0, v74
	v_pk_mul_f32 v[80:81], v[80:81], v[146:147] op_sel_hi:[1,0]
	v_max_f32_e32 v75, 0, v75
	v_max_f32_e32 v76, 0, v76
	v_max_f32_e32 v78, 0, v78
	v_max_f32_e32 v77, 0, v77
	v_pk_mul_f32 v[68:69], v[68:69], v[146:147] op_sel_hi:[1,0]
	v_pk_mul_f32 v[66:67], v[66:67], v[146:147] op_sel_hi:[1,0]
	v_mul_f32_e32 v78, v78, v78
	v_mul_f32_e32 v77, v77, v77
	v_pk_mul_f32 v[72:73], v[72:73], v[146:147] op_sel_hi:[1,0]
	v_pk_mul_f32 v[70:71], v[70:71], v[146:147] op_sel_hi:[1,0]
	v_readlane_b32 s0, v249, 30
	v_readlane_b32 s1, v249, 31
	v_max_f32_e32 v66, 0, v66
	v_lshl_add_u32 v132, s52, 8, v181
	v_ashrrev_i32_e32 v133, 31, v132
	v_lshlrev_b64 v[136:137], 13, v[174:175]
	v_mul_f32_e32 v131, v122, v122
	v_max_f32_e32 v122, 0, v127
	v_lshl_add_u64 v[136:137], s[0:1], 0, v[136:137]
	v_lshlrev_b64 v[132:133], 1, v[132:133]
	v_mul_f32_e32 v122, v122, v122
	v_mul_f32_e32 v127, v123, v123
	v_max_f32_e32 v123, 0, v128
	v_mul_f32_e32 v128, v124, v124
	v_max_f32_e32 v124, 0, v129
	v_lshl_add_u64 v[136:137], v[136:137], 0, v[132:133]
	v_mul_f32_e32 v123, v123, v123
	v_mul_f32_e32 v124, v124, v124
	v_cvt_pk_bf16_f32 v122, v126, v122
	v_cvt_pk_bf16_f32 v123, v123, v124
	v_cvt_pk_bf16_f32 v124, v131, v127
	v_cvt_pk_bf16_f32 v125, v128, v125
	global_store_dwordx4 v[136:137], v[122:125], off
	v_max_f32_e32 v67, 0, v67
	v_max_f32_e32 v68, 0, v68
	v_mul_f32_e32 v122, v114, v114
	v_max_f32_e32 v114, 0, v119
	v_mul_f32_e32 v119, v115, v115
	v_max_f32_e32 v115, 0, v120
	v_mul_f32_e32 v120, v116, v116
	v_max_f32_e32 v116, 0, v121
	v_mul_f32_e32 v114, v114, v114
	v_mul_f32_e32 v115, v115, v115
	v_mul_f32_e32 v116, v116, v116
	v_cvt_pk_bf16_f32 v114, v118, v114
	v_cvt_pk_bf16_f32 v115, v115, v116
	v_cvt_pk_bf16_f32 v116, v122, v119
	v_cvt_pk_bf16_f32 v117, v120, v117
	global_store_dwordx4 v[136:137], v[114:117], off offset:256
	v_max_f32_e32 v70, 0, v70
	v_max_f32_e32 v69, 0, v69
	v_lshlrev_b64 v[114:115], 13, v[172:173]
	v_mul_f32_e32 v116, v106, v106
	v_max_f32_e32 v106, 0, v111
	v_lshl_add_u64 v[114:115], s[0:1], 0, v[114:115]
	v_mul_f32_e32 v106, v106, v106
	v_mul_f32_e32 v111, v107, v107
	v_max_f32_e32 v107, 0, v112
	v_mul_f32_e32 v112, v108, v108
	v_max_f32_e32 v108, 0, v113
	v_lshl_add_u64 v[114:115], v[114:115], 0, v[132:133]
	v_mul_f32_e32 v107, v107, v107
	v_mul_f32_e32 v108, v108, v108
	v_cvt_pk_bf16_f32 v106, v110, v106
	v_cvt_pk_bf16_f32 v107, v107, v108
	v_cvt_pk_bf16_f32 v108, v116, v111
	v_cvt_pk_bf16_f32 v109, v112, v109
	global_store_dwordx4 v[114:115], v[106:109], off
	v_pk_mul_f32 v[56:57], v[56:57], v[142:143] op_sel_hi:[1,0]
	v_mul_f32_e32 v70, v70, v70
	v_mul_f32_e32 v106, v98, v98
	v_max_f32_e32 v98, 0, v103
	v_mul_f32_e32 v103, v99, v99
	v_max_f32_e32 v99, 0, v104
	v_mul_f32_e32 v104, v100, v100
	v_max_f32_e32 v100, 0, v105
	v_mul_f32_e32 v98, v98, v98
	v_mul_f32_e32 v99, v99, v99
	v_mul_f32_e32 v100, v100, v100
	v_cvt_pk_bf16_f32 v98, v102, v98
	v_cvt_pk_bf16_f32 v99, v99, v100
	v_cvt_pk_bf16_f32 v100, v106, v103
	v_cvt_pk_bf16_f32 v101, v104, v101
	global_store_dwordx4 v[114:115], v[98:101], off offset:256
	v_mul_f32_e32 v69, v69, v69
	v_pk_mul_f32 v[60:61], v[60:61], v[142:143] op_sel_hi:[1,0]
	v_lshlrev_b64 v[98:99], 13, v[170:171]
	v_mul_f32_e32 v100, v90, v90
	v_max_f32_e32 v90, 0, v95
	v_lshl_add_u64 v[98:99], s[0:1], 0, v[98:99]
	v_mul_f32_e32 v90, v90, v90
	v_mul_f32_e32 v95, v91, v91
	v_max_f32_e32 v91, 0, v96
	v_mul_f32_e32 v96, v92, v92
	v_max_f32_e32 v92, 0, v97
	v_lshl_add_u64 v[98:99], v[98:99], 0, v[132:133]
	v_mul_f32_e32 v91, v91, v91
	v_mul_f32_e32 v92, v92, v92
	v_cvt_pk_bf16_f32 v90, v94, v90
	v_cvt_pk_bf16_f32 v91, v91, v92
	v_cvt_pk_bf16_f32 v92, v100, v95
	v_cvt_pk_bf16_f32 v93, v96, v93
	global_store_dwordx4 v[98:99], v[90:93], off
	v_pk_mul_f32 v[58:59], v[58:59], v[142:143] op_sel_hi:[1,0]
	v_max_f32_e32 v56, 0, v56
	v_mul_f32_e32 v90, v82, v82
	v_max_f32_e32 v82, 0, v87
	v_mul_f32_e32 v87, v83, v83
	v_max_f32_e32 v83, 0, v88
	v_mul_f32_e32 v88, v84, v84
	v_max_f32_e32 v84, 0, v89
	v_mul_f32_e32 v82, v82, v82
	v_mul_f32_e32 v83, v83, v83
	v_mul_f32_e32 v84, v84, v84
	v_cvt_pk_bf16_f32 v82, v86, v82
	v_cvt_pk_bf16_f32 v83, v83, v84
	v_cvt_pk_bf16_f32 v84, v90, v87
	v_cvt_pk_bf16_f32 v85, v88, v85
	global_store_dwordx4 v[98:99], v[82:85], off offset:256
	v_pk_mul_f32 v[62:63], v[62:63], v[142:143] op_sel_hi:[1,0]
	v_max_f32_e32 v57, 0, v57
	v_lshlrev_b64 v[82:83], 13, v[168:169]
	v_mul_f32_e32 v84, v74, v74
	v_max_f32_e32 v74, 0, v79
	v_lshl_add_u64 v[82:83], s[0:1], 0, v[82:83]
	v_mul_f32_e32 v74, v74, v74
	v_mul_f32_e32 v79, v75, v75
	v_max_f32_e32 v75, 0, v80
	v_mul_f32_e32 v80, v76, v76
	v_max_f32_e32 v76, 0, v81
	v_lshl_add_u64 v[82:83], v[82:83], 0, v[132:133]
	v_mul_f32_e32 v75, v75, v75
	v_mul_f32_e32 v76, v76, v76
	v_cvt_pk_bf16_f32 v74, v78, v74
	v_cvt_pk_bf16_f32 v75, v75, v76
	v_cvt_pk_bf16_f32 v76, v84, v79
	v_cvt_pk_bf16_f32 v77, v80, v77
	global_store_dwordx4 v[82:83], v[74:77], off
	v_max_f32_e32 v58, 0, v58
	v_max_f32_e32 v60, 0, v60
	v_mul_f32_e32 v74, v66, v66
	v_max_f32_e32 v66, 0, v71
	v_mul_f32_e32 v71, v67, v67
	v_max_f32_e32 v67, 0, v72
	v_mul_f32_e32 v72, v68, v68
	v_max_f32_e32 v68, 0, v73
	v_mul_f32_e32 v66, v66, v66
	v_mul_f32_e32 v67, v67, v67
	v_mul_f32_e32 v68, v68, v68
	v_cvt_pk_bf16_f32 v66, v70, v66
	v_cvt_pk_bf16_f32 v67, v67, v68
	v_cvt_pk_bf16_f32 v68, v74, v71
	v_cvt_pk_bf16_f32 v69, v72, v69
	global_store_dwordx4 v[82:83], v[66:69], off offset:256
	v_max_f32_e32 v59, 0, v59
	v_pk_mul_f32 v[50:51], v[50:51], v[142:143] op_sel_hi:[1,0]
	v_lshlrev_b64 v[66:67], 13, v[166:167]
	v_mul_f32_e32 v68, v56, v56
	v_max_f32_e32 v56, 0, v61
	v_lshl_add_u64 v[66:67], s[0:1], 0, v[66:67]
	v_mul_f32_e32 v56, v56, v56
	v_mul_f32_e32 v61, v57, v57
	v_max_f32_e32 v57, 0, v62
	v_mul_f32_e32 v62, v58, v58
	v_max_f32_e32 v58, 0, v63
	v_pk_mul_f32 v[48:49], v[48:49], v[142:143] op_sel_hi:[1,0]
	v_lshl_add_u64 v[66:67], v[66:67], 0, v[132:133]
	v_mul_f32_e32 v60, v60, v60
	v_mul_f32_e32 v57, v57, v57
	v_mul_f32_e32 v58, v58, v58
	v_mul_f32_e32 v59, v59, v59
	v_cvt_pk_bf16_f32 v56, v60, v56
	v_pk_mul_f32 v[54:55], v[54:55], v[142:143] op_sel_hi:[1,0]
	v_pk_mul_f32 v[52:53], v[52:53], v[142:143] op_sel_hi:[1,0]
	v_max_f32_e32 v48, 0, v48
	v_max_f32_e32 v49, 0, v49
	v_max_f32_e32 v50, 0, v50
	v_cvt_pk_bf16_f32 v57, v57, v58
	v_cvt_pk_bf16_f32 v58, v68, v61
	v_cvt_pk_bf16_f32 v59, v62, v59
	global_store_dwordx4 v[66:67], v[56:59], off
	v_max_f32_e32 v52, 0, v52
	v_max_f32_e32 v51, 0, v51
	v_mul_f32_e32 v56, v48, v48
	v_max_f32_e32 v48, 0, v53
	v_mul_f32_e32 v53, v49, v49
	v_max_f32_e32 v49, 0, v54
	v_mul_f32_e32 v54, v50, v50
	v_max_f32_e32 v50, 0, v55
	v_mul_f32_e32 v48, v48, v48
	v_mul_f32_e32 v49, v49, v49
	v_mul_f32_e32 v50, v50, v50
	v_pk_mul_f32 v[40:41], v[40:41], v[138:139] op_sel_hi:[1,0]
	v_mul_f32_e32 v52, v52, v52
	v_mul_f32_e32 v51, v51, v51
	v_cvt_pk_bf16_f32 v48, v52, v48
	v_cvt_pk_bf16_f32 v49, v49, v50
	v_cvt_pk_bf16_f32 v50, v56, v53
	v_pk_mul_f32 v[44:45], v[44:45], v[138:139] op_sel_hi:[1,0]
	v_pk_mul_f32 v[42:43], v[42:43], v[138:139] op_sel_hi:[1,0]
	v_max_f32_e32 v40, 0, v40
	v_cvt_pk_bf16_f32 v51, v54, v51
	global_store_dwordx4 v[66:67], v[48:51], off offset:256
	v_pk_mul_f32 v[46:47], v[46:47], v[138:139] op_sel_hi:[1,0]
	v_max_f32_e32 v41, 0, v41
	v_lshlrev_b64 v[48:49], 13, v[164:165]
	v_mul_f32_e32 v50, v40, v40
	v_max_f32_e32 v40, 0, v45
	v_max_f32_e32 v42, 0, v42
	v_lshl_add_u64 v[48:49], s[0:1], 0, v[48:49]
	v_max_f32_e32 v44, 0, v44
	v_mul_f32_e32 v40, v40, v40
	v_mul_f32_e32 v45, v41, v41
	v_max_f32_e32 v41, 0, v46
	v_mul_f32_e32 v46, v42, v42
	v_max_f32_e32 v42, 0, v47
	v_max_f32_e32 v43, 0, v43
	v_pk_mul_f32 v[34:35], v[34:35], v[138:139] op_sel_hi:[1,0]
	v_pk_mul_f32 v[32:33], v[32:33], v[138:139] op_sel_hi:[1,0]
	v_lshl_add_u64 v[48:49], v[48:49], 0, v[132:133]
	v_mul_f32_e32 v44, v44, v44
	v_mul_f32_e32 v41, v41, v41
	v_mul_f32_e32 v42, v42, v42
	v_mul_f32_e32 v43, v43, v43
	v_cvt_pk_bf16_f32 v40, v44, v40
	v_pk_mul_f32 v[38:39], v[38:39], v[138:139] op_sel_hi:[1,0]
	v_pk_mul_f32 v[36:37], v[36:37], v[138:139] op_sel_hi:[1,0]
	v_max_f32_e32 v32, 0, v32
	v_max_f32_e32 v33, 0, v33
	v_max_f32_e32 v34, 0, v34
	v_cvt_pk_bf16_f32 v41, v41, v42
	v_cvt_pk_bf16_f32 v42, v50, v45
	v_cvt_pk_bf16_f32 v43, v46, v43
	global_store_dwordx4 v[48:49], v[40:43], off
	v_max_f32_e32 v36, 0, v36
	v_max_f32_e32 v35, 0, v35
	v_mul_f32_e32 v40, v32, v32
	v_max_f32_e32 v32, 0, v37
	v_mul_f32_e32 v37, v33, v33
	v_max_f32_e32 v33, 0, v38
	v_mul_f32_e32 v38, v34, v34
	v_max_f32_e32 v34, 0, v39
	v_mul_f32_e32 v32, v32, v32
	v_mul_f32_e32 v33, v33, v33
	v_mul_f32_e32 v34, v34, v34
	v_pk_mul_f32 v[24:25], v[24:25], v[134:135] op_sel_hi:[1,0]
	v_mul_f32_e32 v36, v36, v36
	v_mul_f32_e32 v35, v35, v35
	v_cvt_pk_bf16_f32 v32, v36, v32
	v_cvt_pk_bf16_f32 v33, v33, v34
	v_cvt_pk_bf16_f32 v34, v40, v37
	v_pk_mul_f32 v[28:29], v[28:29], v[134:135] op_sel_hi:[1,0]
	v_pk_mul_f32 v[26:27], v[26:27], v[134:135] op_sel_hi:[1,0]
	v_max_f32_e32 v24, 0, v24
	v_cvt_pk_bf16_f32 v35, v38, v35
	global_store_dwordx4 v[48:49], v[32:35], off offset:256
	v_pk_mul_f32 v[30:31], v[30:31], v[134:135] op_sel_hi:[1,0]
	v_max_f32_e32 v25, 0, v25
	v_lshlrev_b64 v[32:33], 13, v[162:163]
	v_mul_f32_e32 v34, v24, v24
	v_max_f32_e32 v24, 0, v29
	v_max_f32_e32 v26, 0, v26
	v_lshl_add_u64 v[32:33], s[0:1], 0, v[32:33]
	v_max_f32_e32 v28, 0, v28
	v_mul_f32_e32 v24, v24, v24
	v_mul_f32_e32 v29, v25, v25
	v_max_f32_e32 v25, 0, v30
	v_mul_f32_e32 v30, v26, v26
	v_max_f32_e32 v26, 0, v31
	v_max_f32_e32 v27, 0, v27
	v_pk_mul_f32 v[18:19], v[18:19], v[134:135] op_sel_hi:[1,0]
	v_pk_mul_f32 v[16:17], v[16:17], v[134:135] op_sel_hi:[1,0]
	v_lshl_add_u64 v[32:33], v[32:33], 0, v[132:133]
	v_mul_f32_e32 v28, v28, v28
	v_mul_f32_e32 v25, v25, v25
	v_mul_f32_e32 v26, v26, v26
	v_mul_f32_e32 v27, v27, v27
	v_cvt_pk_bf16_f32 v24, v28, v24
	v_pk_mul_f32 v[22:23], v[22:23], v[134:135] op_sel_hi:[1,0]
	v_pk_mul_f32 v[20:21], v[20:21], v[134:135] op_sel_hi:[1,0]
	v_max_f32_e32 v16, 0, v16
	v_max_f32_e32 v17, 0, v17
	v_max_f32_e32 v18, 0, v18
	v_cvt_pk_bf16_f32 v25, v25, v26
	v_cvt_pk_bf16_f32 v26, v34, v29
	v_cvt_pk_bf16_f32 v27, v30, v27
	global_store_dwordx4 v[32:33], v[24:27], off
	v_max_f32_e32 v20, 0, v20
	v_max_f32_e32 v19, 0, v19
	v_mul_f32_e32 v24, v16, v16
	v_max_f32_e32 v16, 0, v21
	v_mul_f32_e32 v21, v17, v17
	v_max_f32_e32 v17, 0, v22
	v_mul_f32_e32 v22, v18, v18
	v_max_f32_e32 v18, 0, v23
	v_mul_f32_e32 v16, v16, v16
	v_mul_f32_e32 v17, v17, v17
	v_mul_f32_e32 v18, v18, v18
	v_pk_mul_f32 v[8:9], v[8:9], v[130:131] op_sel_hi:[1,0]
	v_mul_f32_e32 v20, v20, v20
	v_mul_f32_e32 v19, v19, v19
	v_cvt_pk_bf16_f32 v16, v20, v16
	v_cvt_pk_bf16_f32 v17, v17, v18
	v_cvt_pk_bf16_f32 v18, v24, v21
	v_pk_mul_f32 v[12:13], v[12:13], v[130:131] op_sel_hi:[1,0]
	v_pk_mul_f32 v[10:11], v[10:11], v[130:131] op_sel_hi:[1,0]
	v_max_f32_e32 v8, 0, v8
	v_cvt_pk_bf16_f32 v19, v22, v19
	global_store_dwordx4 v[32:33], v[16:19], off offset:256
	v_pk_mul_f32 v[14:15], v[14:15], v[130:131] op_sel_hi:[1,0]
	v_max_f32_e32 v9, 0, v9
	v_lshlrev_b64 v[16:17], 13, v[160:161]
	v_mul_f32_e32 v18, v8, v8
	v_max_f32_e32 v8, 0, v13
	v_max_f32_e32 v10, 0, v10
	v_lshl_add_u64 v[16:17], s[0:1], 0, v[16:17]
	v_max_f32_e32 v12, 0, v12
	v_mul_f32_e32 v8, v8, v8
	v_mul_f32_e32 v13, v9, v9
	v_max_f32_e32 v9, 0, v14
	v_mul_f32_e32 v14, v10, v10
	v_max_f32_e32 v10, 0, v15
	v_max_f32_e32 v11, 0, v11
	v_pk_mul_f32 v[2:3], v[2:3], v[130:131] op_sel_hi:[1,0]
	v_pk_mul_f32 v[0:1], v[0:1], v[130:131] op_sel_hi:[1,0]
	v_lshl_add_u64 v[16:17], v[16:17], 0, v[132:133]
	v_mul_f32_e32 v12, v12, v12
	v_mul_f32_e32 v9, v9, v9
	v_mul_f32_e32 v10, v10, v10
	v_mul_f32_e32 v11, v11, v11
	v_cvt_pk_bf16_f32 v8, v12, v8
	v_pk_mul_f32 v[6:7], v[6:7], v[130:131] op_sel_hi:[1,0]
	v_pk_mul_f32 v[4:5], v[4:5], v[130:131] op_sel_hi:[1,0]
	v_max_f32_e32 v0, 0, v0
	v_max_f32_e32 v1, 0, v1
	v_max_f32_e32 v2, 0, v2
	v_cvt_pk_bf16_f32 v9, v9, v10
	v_cvt_pk_bf16_f32 v10, v18, v13
	v_cvt_pk_bf16_f32 v11, v14, v11
	global_store_dwordx4 v[16:17], v[8:11], off
	v_max_f32_e32 v3, 0, v3
	v_max_f32_e32 v4, 0, v4
	v_mul_f32_e32 v8, v0, v0
	v_max_f32_e32 v0, 0, v5
	v_mul_f32_e32 v5, v1, v1
	v_max_f32_e32 v1, 0, v6
	v_mul_f32_e32 v6, v2, v2
	v_max_f32_e32 v2, 0, v7
	v_mul_f32_e32 v0, v0, v0
	v_mul_f32_e32 v1, v1, v1
	v_mul_f32_e32 v2, v2, v2
	v_mul_f32_e32 v3, v3, v3
	s_mov_b64 s[0:1], -1
	s_andn2_b64 vcc, exec, s[42:43]
	v_mul_f32_e32 v4, v4, v4
	v_cvt_pk_bf16_f32 v0, v4, v0
	v_cvt_pk_bf16_f32 v1, v1, v2
	v_cvt_pk_bf16_f32 v2, v8, v5
	v_cvt_pk_bf16_f32 v3, v6, v3
	global_store_dwordx4 v[16:17], v[0:3], off offset:256
	s_branch .Lff1_join
